# v15 + the no-op s_setprio 0 x4 of the attention pp4 loop and the pre-loop raise they cancel removed (priorities unchanged, 4 SALU fewer per tile next to the barriers)
# speedup vs baseline: 1.0024x; 1.0024x over previous
.LBB0_749:
	s_and_b64 vcc, exec, s[8:9]
	s_cbranch_vccz .LBB0_710
	v_mov_b32_e32 v2, v0
	s_lshr_b32 s2, s21, 26
	v_ashrrev_i32_e32 v4, 4, v2
	v_ashrrev_i32_e32 v5, 31, v4
	s_add_i32 s2, s20, s2
	v_add_u32_e32 v3, 0x200, v2
	v_lshlrev_b64 v[6:7], 8, v[4:5]
	v_xor_b32_e32 v4, v4, v2
	s_ashr_i32 s2, s2, 6
	v_lshlrev_b32_e32 v8, 4, v4
	v_ashrrev_i32_e32 v4, 4, v3
	s_ashr_i32 s3, s2, 31
	s_lshl_b64 s[8:9], s[44:45], 23
	v_lshl_add_u64 v[6:7], s[42:43], 0, v[6:7]
	v_and_b32_e32 v228, 0xf0, v8
	v_ashrrev_i32_e32 v5, 31, v4
	s_add_u32 s8, s40, s8
	v_lshl_add_u64 v[146:147], v[6:7], 0, v[228:229]
	v_lshlrev_b64 v[6:7], 8, v[4:5]
	v_xor_b32_e32 v4, v4, v2
	s_addc_u32 s9, s41, s9
	s_lshl_b64 s[2:3], s[2:3], 14
	v_lshlrev_b32_e32 v9, 4, v4
	v_lshlrev_b32_e32 v4, 3, v2
	s_add_u32 s8, s8, s2
	v_and_b32_e32 v4, 0xffffffc0, v4
	s_addc_u32 s9, s9, s3
	v_lshl_add_u64 v[6:7], s[42:43], 0, v[6:7]
	v_and_b32_e32 v228, 0xf0, v9
	v_ashrrev_i32_e32 v5, 31, v4
	v_lshl_add_u64 v[148:149], v[6:7], 0, v[228:229]
	v_lshl_add_u64 v[4:5], v[4:5], 1, s[8:9]
	v_and_b32_e32 v228, 0x70, v8
	v_lshlrev_b32_e32 v3, 3, v3
	v_readfirstlane_b32 s3, v2
	v_lshl_add_u64 v[150:151], v[4:5], 0, v[228:229]
	v_and_b32_e32 v4, 0xffffffc0, v3
	s_ashr_i32 s12, s3, 6
	v_ashrrev_i32_e32 v5, 31, v4
	v_and_b32_e32 v156, 31, v2
	v_lshl_add_u64 v[4:5], v[4:5], 1, s[8:9]
	v_and_b32_e32 v228, 0x70, v9
	s_lshl_b32 s2, s12, 5
	v_bfe_u32 v157, v2, 5, 1
	v_lshl_add_u64 v[152:153], v[4:5], 0, v[228:229]
	v_or_b32_e32 v3, s2, v156
	v_mov_b64_e32 v[4:5], s[28:29]
	v_lshlrev_b32_e32 v228, 4, v157
	v_mad_i64_i32 v[4:5], s[8:9], v3, s53, v[4:5]
	v_lshl_add_u64 v[4:5], v[4:5], 0, v[228:229]
	global_load_dwordx4 v[98:101], v[4:5], off
	global_load_dwordx4 v[102:105], v[4:5], off offset:32
	s_lshl_b32 s8, s12, 10
	s_add_i32 s8, s8, 0
	global_load_dwordx4 v[106:109], v[4:5], off offset:64
	s_mov_b32 m0, s8
	v_lshl_add_u64 v[6:7], v[146:147], 0, s[0:1]
	global_load_lds_dwordx4 v[146:147], off
	s_add_i32 m0, s8, 0x2000
	v_lshlrev_b32_e32 v3, 8, v156
	global_load_lds_dwordx4 v[148:149], off
	s_add_i32 m0, s8, 0x4000
	v_add_u32_e32 v14, 0, v3
	global_load_lds_dwordx4 v[6:7], off
	v_lshl_add_u64 v[6:7], v[148:149], 0, s[0:1]
	s_add_i32 m0, s8, 0x6000
	s_nop 0
	global_load_lds_dwordx4 v[6:7], off
	v_lshl_add_u64 v[6:7], v[146:147], 0, s[4:5]
	s_add_i32 m0, s8, 0x8000
	s_nop 0
	global_load_lds_dwordx4 v[6:7], off
	v_lshl_add_u64 v[6:7], v[148:149], 0, s[4:5]
	s_add_i32 m0, s8, 0xa000
	s_nop 0
	global_load_lds_dwordx4 v[6:7], off
	s_add_i32 m0, s8, 0xc000
	v_lshl_add_u64 v[6:7], v[150:151], 0, s[0:1]
	global_load_lds_dwordx4 v[150:151], off
	s_add_i32 m0, s8, 0xe000
	s_nop 0
	global_load_lds_dwordx4 v[152:153], off
	s_add_i32 m0, s8, 0x10000
	s_nop 0
	global_load_lds_dwordx4 v[6:7], off
	v_lshl_add_u64 v[6:7], v[152:153], 0, s[0:1]
	s_add_i32 m0, s8, 0x12000
	s_cmp_lt_i32 s12, 4
	global_load_lds_dwordx4 v[6:7], off
	global_load_dwordx4 v[110:113], v[4:5], off offset:96
	global_load_dwordx4 v[114:117], v[4:5], off offset:128
	global_load_dwordx4 v[118:121], v[4:5], off offset:160
	global_load_dwordx4 v[122:125], v[4:5], off offset:192
	global_load_dwordx4 v[126:129], v[4:5], off offset:224
	v_lshlrev_b32_e32 v4, 4, v2
	s_waitcnt vmcnt(0)
	v_and_b32_e32 v5, 0xf0, v4
	s_waitcnt lgkmcnt(0)
	s_barrier
	v_xad_u32 v10, v228, v5, v14
	ds_read_b128 v[6:9], v10
	ds_read_b128 v[10:13], v10 offset:8192
	s_waitcnt vmcnt(0) lgkmcnt(0)
	v_mfma_f32_32x32x16_bf16 v[82:97], v[6:9], v[98:101], 0
	v_or_b32_e32 v6, 32, v228
	s_cselect_b64 s[28:29], -1, 0
	s_and_b64 vcc, exec, s[28:29]
	v_mfma_f32_32x32x16_bf16 v[66:81], v[10:13], v[98:101], 0
	v_xad_u32 v10, v6, v5, v14
	ds_read_b128 v[6:9], v10
	ds_read_b128 v[10:13], v10 offset:8192
	s_waitcnt lgkmcnt(1)
	v_mfma_f32_32x32x16_bf16 v[82:97], v[6:9], v[102:105], v[82:97]
	v_or_b32_e32 v6, 64, v228
	s_waitcnt lgkmcnt(0)
	v_mfma_f32_32x32x16_bf16 v[66:81], v[10:13], v[102:105], v[66:81]
	v_xad_u32 v10, v6, v5, v14
	ds_read_b128 v[6:9], v10
	ds_read_b128 v[10:13], v10 offset:8192
	s_waitcnt lgkmcnt(1)
	v_mfma_f32_32x32x16_bf16 v[82:97], v[6:9], v[106:109], v[82:97]
	v_or_b32_e32 v6, 0x60, v228
	s_waitcnt lgkmcnt(0)
	v_mfma_f32_32x32x16_bf16 v[66:81], v[10:13], v[106:109], v[66:81]
	v_xad_u32 v10, v6, v5, v14
	ds_read_b128 v[6:9], v10
	ds_read_b128 v[10:13], v10 offset:8192
	s_waitcnt lgkmcnt(1)
	v_mfma_f32_32x32x16_bf16 v[82:97], v[6:9], v[110:113], v[82:97]
	v_or_b32_e32 v6, 0x80, v228
	s_waitcnt lgkmcnt(0)
	v_mfma_f32_32x32x16_bf16 v[66:81], v[10:13], v[110:113], v[66:81]
	v_xad_u32 v10, v6, v5, v14
	ds_read_b128 v[6:9], v10
	ds_read_b128 v[10:13], v10 offset:8192
	s_waitcnt lgkmcnt(1)
	v_mfma_f32_32x32x16_bf16 v[82:97], v[6:9], v[114:117], v[82:97]
	v_or_b32_e32 v6, 0xa0, v228
	s_waitcnt lgkmcnt(0)
	v_mfma_f32_32x32x16_bf16 v[66:81], v[10:13], v[114:117], v[66:81]
	v_xad_u32 v10, v6, v5, v14
	ds_read_b128 v[6:9], v10
	ds_read_b128 v[10:13], v10 offset:8192
	s_waitcnt lgkmcnt(1)
	v_mfma_f32_32x32x16_bf16 v[82:97], v[6:9], v[118:121], v[82:97]
	v_or_b32_e32 v6, 0xc0, v228
	s_waitcnt lgkmcnt(0)
	v_mfma_f32_32x32x16_bf16 v[66:81], v[10:13], v[118:121], v[66:81]
	v_xad_u32 v10, v6, v5, v14
	ds_read_b128 v[6:9], v10
	ds_read_b128 v[10:13], v10 offset:8192
	s_waitcnt lgkmcnt(1)
	v_mfma_f32_32x32x16_bf16 v[82:97], v[6:9], v[122:125], v[82:97]
	v_or_b32_e32 v6, 0xe0, v228
	v_xad_u32 v5, v6, v5, v14
	s_waitcnt lgkmcnt(0)
	v_mfma_f32_32x32x16_bf16 v[66:81], v[10:13], v[122:125], v[66:81]
	ds_read_b128 v[6:9], v5
	ds_read_b128 v[10:13], v5 offset:8192
	s_waitcnt lgkmcnt(1)
	v_mfma_f32_32x32x16_bf16 v[82:97], v[6:9], v[126:129], v[82:97]
	s_waitcnt lgkmcnt(0)
	v_mfma_f32_32x32x16_bf16 v[66:81], v[10:13], v[126:129], v[66:81]
	s_cbranch_vccnz .LBB0_752
	s_waitcnt lgkmcnt(0)
	s_barrier
.LBB0_752:
	s_cmp_lg_u32 0, -1
	s_cselect_b32 s21, 0, 0
	v_bitop3_b32 v8, v228, v4, 16 bitop3:0x78
	v_add3_u32 v158, v3, s21, v8
	s_add_i32 s21, s21, 0xc000
	v_lshl_add_u32 v3, v156, 7, s21
	s_ashr_i32 s21, s94, 31
	s_lshr_b32 s21, s21, 26
	v_lshrrev_b32_e32 v5, 1, v2
	v_bfe_u32 v2, v2, 1, 3
	s_add_i32 s21, s94, s21
	v_bitop3_b32 v5, v157, v5, 7 bitop3:0x78
	v_bitop3_b32 v6, v157, v2, 2 bitop3:0x36
	v_bitop3_b32 v7, v157, v2, 4 bitop3:0x36
	v_bitop3_b32 v2, v157, v2, 6 bitop3:0x36
	s_ashr_i32 s21, s21, 6
	v_mov_b32_e32 v155, 0
	s_mov_b32 s9, 1
	s_mov_b32 s12, 2
	s_mov_b32 s13, 0
	v_lshl_add_u32 v159, v5, 4, v3
	v_lshl_add_u32 v160, v6, 4, v3
	v_lshl_add_u32 v161, v7, 4, v3
	v_lshl_add_u32 v162, v2, 4, v3
	v_and_b32_e32 v163, 0xe0, v4
	s_add_i32 s22, s21, -1
	s_mov_b32 s23, 0
	s_mov_b32 s42, 0
	v_mov_b32_e32 v2, v155
	v_mov_b32_e32 v3, v155
	v_mov_b32_e32 v4, v155
	v_mov_b32_e32 v5, v155
	v_mov_b32_e32 v6, v155
	v_mov_b32_e32 v7, v155
	v_mov_b32_e32 v8, v155
	v_mov_b32_e32 v9, v155
	v_mov_b32_e32 v10, v155
	v_mov_b32_e32 v11, v155
	v_mov_b32_e32 v12, v155
	v_mov_b32_e32 v13, v155
	v_mov_b32_e32 v14, v155
	v_mov_b32_e32 v15, v155
	v_mov_b32_e32 v16, v155
	v_mov_b32_e32 v17, v155
	v_mov_b32_e32 v18, v155
	v_mov_b32_e32 v19, v155
	v_mov_b32_e32 v20, v155
	v_mov_b32_e32 v21, v155
	v_mov_b32_e32 v22, v155
	v_mov_b32_e32 v23, v155
	v_mov_b32_e32 v24, v155
	v_mov_b32_e32 v25, v155
	v_mov_b32_e32 v26, v155
	v_mov_b32_e32 v27, v155
	v_mov_b32_e32 v28, v155
	v_mov_b32_e32 v29, v155
	v_mov_b32_e32 v30, v155
	v_mov_b32_e32 v31, v155
	v_mov_b32_e32 v32, v155
	v_mov_b32_e32 v33, v155
	v_mov_b32_e32 v34, v155
	v_mov_b32_e32 v35, v155
	v_mov_b32_e32 v36, v155
	v_mov_b32_e32 v37, v155
	v_mov_b32_e32 v38, v155
	v_mov_b32_e32 v39, v155
	v_mov_b32_e32 v40, v155
	v_mov_b32_e32 v41, v155
	v_mov_b32_e32 v42, v155
	v_mov_b32_e32 v43, v155
	v_mov_b32_e32 v44, v155
	v_mov_b32_e32 v45, v155
	v_mov_b32_e32 v46, v155
	v_mov_b32_e32 v47, v155
	v_mov_b32_e32 v48, v155
	v_mov_b32_e32 v49, v155
	v_mov_b32_e32 v50, v155
	v_mov_b32_e32 v51, v155
	v_mov_b32_e32 v52, v155
	v_mov_b32_e32 v53, v155
	v_mov_b32_e32 v54, v155
	v_mov_b32_e32 v55, v155
	v_mov_b32_e32 v56, v155
	v_mov_b32_e32 v57, v155
	v_mov_b32_e32 v58, v155
	v_mov_b32_e32 v59, v155
	v_mov_b32_e32 v60, v155
	v_mov_b32_e32 v61, v155
	v_mov_b32_e32 v62, v155
	v_mov_b32_e32 v63, v155
	v_mov_b32_e32 v64, v155
	v_mov_b32_e32 v65, v155
.LBB0_753:
	s_lshl_b32 s43, s13, 14
	v_add_u32_e32 v142, s43, v159
	v_add_u32_e32 v143, s43, v160
	v_add_u32_e32 v144, s43, v161
	v_add_u32_e32 v154, s43, v162
	ds_read_b128 v[164:167], v142 offset:0
	ds_read_b128 v[168:171], v143 offset:0
	ds_read_b128 v[172:175], v144 offset:0
	ds_read_b128 v[130:133], v154 offset:0
	ds_read_b128 v[176:179], v142 offset:0x1000
	ds_read_b128 v[180:183], v143 offset:0x1000
	ds_read_b128 v[184:187], v144 offset:0x1000
	ds_read_b128 v[134:137], v154 offset:0x1000
	ds_read_b128 v[188:191], v142 offset:0x2000
	ds_read_b128 v[192:195], v143 offset:0x2000
	ds_read_b128 v[196:199], v144 offset:0x2000
	ds_read_b128 v[138:141], v154 offset:0x2000
	ds_read_b128 v[200:203], v142 offset:0x3000
	ds_read_b128 v[204:207], v143 offset:0x3000
	ds_read_b128 v[208:211], v144 offset:0x3000
	ds_read_b128 v[142:145], v154 offset:0x3000
	v_exp_f32_e32 v90, v90
	v_exp_f32_e32 v212, v91
	v_exp_f32_e32 v91, v92
	v_exp_f32_e32 v213, v93
	v_exp_f32_e32 v92, v94
	v_exp_f32_e32 v94, v95
	v_exp_f32_e32 v93, v96
	v_exp_f32_e32 v95, v97
	v_exp_f32_e32 v82, v82
	v_exp_f32_e32 v83, v83
	v_exp_f32_e32 v84, v84
	v_exp_f32_e32 v85, v85
	v_pk_add_f32 v[96:97], v[90:91], v[212:213]
	v_pk_add_f32 v[214:215], v[92:93], v[94:95]
	v_pk_add_f32 v[96:97], v[96:97], v[96:97] op_sel_hi:[0,1]
	v_cvt_pk_bf16_f32 v90, v90, v212
	v_cvt_pk_bf16_f32 v91, v91, v213
	v_cvt_pk_bf16_f32 v92, v92, v94
	v_exp_f32_e32 v86, v86
	v_exp_f32_e32 v94, v87
	v_exp_f32_e32 v88, v88
	v_exp_f32_e32 v96, v89
	v_cvt_pk_bf16_f32 v93, v93, v95
	v_add_f32_e32 v87, v82, v83
	v_add_f32_e32 v89, v84, v85
	v_cvt_pk_bf16_f32 v82, v82, v83
	v_cvt_pk_bf16_f32 v83, v84, v85
	v_cvt_pk_bf16_f32 v84, v86, v94
	v_cvt_pk_bf16_f32 v85, v88, v96
	s_waitcnt lgkmcnt(0)
	s_barrier
	v_permlane32_swap_b32_e32 v90, v92
	v_permlane32_swap_b32_e32 v91, v93
	v_add_f32_e32 v95, v86, v94
	v_permlane32_swap_b32_e32 v82, v84
	v_permlane32_swap_b32_e32 v83, v85
	v_pk_add_f32 v[214:215], v[214:215], v[214:215] op_sel_hi:[0,1]
	v_add_f32_e32 v213, v88, v96
	v_mfma_f32_32x32x16_bf16 v[50:65], v[82:85], v[164:167], v[50:65]
	v_mfma_f32_32x32x16_bf16 v[34:49], v[82:85], v[176:179], v[34:49]
	v_mfma_f32_32x32x16_bf16 v[18:33], v[82:85], v[188:191], v[18:33]
	v_mfma_f32_32x32x16_bf16 v[2:17], v[82:85], v[200:203], v[2:17]
	v_exp_f32_e32 v86, v66
	v_exp_f32_e32 v88, v67
	v_exp_f32_e32 v94, v68
	v_exp_f32_e32 v212, v69
	v_mfma_f32_32x32x16_bf16 v[50:65], v[90:93], v[168:171], v[50:65]
	v_exp_f32_e32 v82, v70
	v_exp_f32_e32 v83, v71
	v_exp_f32_e32 v96, v72
	v_exp_f32_e32 v214, v73
	v_pk_add_f32 v[66:67], v[86:87], v[88:89]
	v_pk_add_f32 v[68:69], v[94:95], v[212:213]
	v_add_f32_e32 v154, v82, v83
	v_mfma_f32_32x32x16_bf16 v[34:49], v[90:93], v[180:183], v[34:49]
	v_add_f32_e64 v66, v66, v68
	v_add_f32_e64 v67, v67, v69
	v_add_f32_e64 v68, v96, v214
	v_add_f32_e64 v69, v97, v215
	v_add_f32_e64 v68, v154, v68
	v_add_f32_e64 v69, v155, v69
	v_pk_add_f32 v[70:71], v[66:67], v[68:69]
	v_cvt_pk_bf16_f32 v66, v86, v88
	v_mfma_f32_32x32x16_bf16 v[18:33], v[90:93], v[192:195], v[18:33]
	v_cvt_pk_bf16_f32 v67, v94, v212
	v_cvt_pk_bf16_f32 v68, v82, v83
	v_cvt_pk_bf16_f32 v69, v96, v214
	s_nop 0
	v_permlane32_swap_b32_e32 v66, v68
	v_permlane32_swap_b32_e32 v67, v69
	v_mfma_f32_32x32x16_bf16 v[2:17], v[90:93], v[204:207], v[2:17]
	v_exp_f32_e32 v72, v74
	v_exp_f32_e32 v74, v75
	v_mfma_f32_32x32x16_bf16 v[50:65], v[66:69], v[172:175], v[50:65]
	v_exp_f32_e32 v76, v76
	v_exp_f32_e32 v82, v77
	v_exp_f32_e32 v73, v78
	v_exp_f32_e32 v75, v79
	v_exp_f32_e32 v77, v80
	v_exp_f32_e32 v83, v81
	v_add_f32_e32 v70, v70, v71
	v_mfma_f32_32x32x16_bf16 v[34:49], v[66:69], v[184:187], v[34:49]
	v_add_f32_e64 v78, v72, v74
	v_add_f32_e64 v79, v73, v75
	v_add_f32_e64 v80, v76, v82
	v_add_f32_e64 v81, v77, v83
	v_cvt_pk_bf16_f32 v164, v72, v74
	v_cvt_pk_bf16_f32 v165, v76, v82
	v_cvt_pk_bf16_f32 v166, v73, v75
	v_cvt_pk_bf16_f32 v167, v77, v83
	v_mfma_f32_32x32x16_bf16 v[18:33], v[66:69], v[196:199], v[18:33]
	v_add_f32_e64 v78, v78, v80
	v_add_f32_e64 v79, v79, v81
	v_permlane32_swap_b32_e32 v164, v166
	v_add_f32_e32 v71, v78, v79
	v_add_f32_e32 v155, v71, v70
	v_permlane32_swap_b32_e32 v165, v167
	v_mfma_f32_32x32x16_bf16 v[2:17], v[66:69], v[208:211], v[2:17]
	s_waitcnt lgkmcnt(0)
	s_barrier
	v_mov_b32_e32 v74, v163
	v_lshl_add_u32 v75, s9, 14, v158
	s_nop 0
	v_add_u32_e32 v76, v74, v75
	ds_read_b128 v[66:69], v76 offset:0
	ds_read_b128 v[70:73], v76 offset:0x2000
	v_xad_u32 v77, v74, 32, v75
	ds_read_b128 v[168:171], v77 offset:0
	ds_read_b128 v[172:175], v77 offset:0x2000
	v_xad_u32 v76, v74, 64, v75
	ds_read_b128 v[176:179], v76 offset:0
	ds_read_b128 v[180:183], v76 offset:0x2000
	v_xad_u32 v77, v74, s66, v75
	ds_read_b128 v[184:187], v77 offset:0
	ds_read_b128 v[188:191], v77 offset:0x2000
	v_xad_u32 v76, v74, s67, v75
	ds_read_b128 v[192:195], v76 offset:0
	ds_read_b128 v[196:199], v76 offset:0x2000
	v_xad_u32 v77, v74, s68, v75
	ds_read_b128 v[200:203], v77 offset:0
	ds_read_b128 v[204:207], v77 offset:0x2000
	v_xad_u32 v76, v74, s69, v75
	ds_read_b128 v[208:211], v76 offset:0
	ds_read_b128 v[212:215], v76 offset:0x2000
	v_xad_u32 v74, v74, s74, v75
	ds_read_b128 v[216:219], v74 offset:0
	ds_read_b128 v[220:223], v74 offset:0x2000
	s_add_i32 s43, s42, 3
	s_min_i32 s44, s43, s22
	s_add_i32 s43, s42, 2
	s_min_i32 s46, s43, s22
	s_ashr_i32 s45, s44, 31
	s_lshl_b32 s43, s23, 14
	s_lshl_b64 s[44:45], s[44:45], 14
	s_add_i32 s43, s8, s43
	s_waitcnt vmcnt(0)
	v_lshl_add_u64 v[74:75], v[146:147], 0, s[44:45]
	s_mov_b32 m0, s43
	s_ashr_i32 s47, s46, 31
	global_load_lds_dwordx4 v[74:75], off
	s_add_i32 m0, s43, 0x2000
	s_lshl_b32 s43, s12, 14
	v_lshl_add_u64 v[74:75], v[148:149], 0, s[44:45]
	s_lshl_b64 s[44:45], s[46:47], 14
	s_add_i32 s43, s8, s43
	global_load_lds_dwordx4 v[74:75], off
	v_lshl_add_u64 v[74:75], v[150:151], 0, s[44:45]
	s_add_i32 m0, s43, 0xc000
	s_nop 0
	global_load_lds_dwordx4 v[74:75], off
	v_lshl_add_u64 v[74:75], v[152:153], 0, s[44:45]
	s_add_i32 m0, s43, 0xe000
	s_nop 0
	global_load_lds_dwordx4 v[74:75], off
	s_waitcnt lgkmcnt(0)
	s_barrier
	v_mfma_f32_32x32x16_bf16 v[82:97], v[66:69], v[98:101], 0
	v_mfma_f32_32x32x16_bf16 v[66:81], v[70:73], v[98:101], 0
	v_mfma_f32_32x32x16_bf16 v[82:97], v[168:171], v[102:105], v[82:97]
	v_mfma_f32_32x32x16_bf16 v[66:81], v[172:175], v[102:105], v[66:81]
	v_mfma_f32_32x32x16_bf16 v[82:97], v[176:179], v[106:109], v[82:97]
	v_mfma_f32_32x32x16_bf16 v[66:81], v[180:183], v[106:109], v[66:81]
	v_mfma_f32_32x32x16_bf16 v[82:97], v[184:187], v[110:113], v[82:97]
	v_mfma_f32_32x32x16_bf16 v[66:81], v[188:191], v[110:113], v[66:81]
	v_mfma_f32_32x32x16_bf16 v[82:97], v[192:195], v[114:117], v[82:97]
	v_mfma_f32_32x32x16_bf16 v[66:81], v[196:199], v[114:117], v[66:81]
	v_mfma_f32_32x32x16_bf16 v[82:97], v[200:203], v[118:121], v[82:97]
	v_mfma_f32_32x32x16_bf16 v[66:81], v[204:207], v[118:121], v[66:81]
	v_mfma_f32_32x32x16_bf16 v[82:97], v[208:211], v[122:125], v[82:97]
	v_mfma_f32_32x32x16_bf16 v[66:81], v[212:215], v[122:125], v[66:81]
	v_mfma_f32_32x32x16_bf16 v[82:97], v[216:219], v[126:129], v[82:97]
	v_mfma_f32_32x32x16_bf16 v[66:81], v[220:223], v[126:129], v[66:81]
	v_mfma_f32_32x32x16_bf16 v[50:65], v[164:167], v[130:133], v[50:65]
	v_mfma_f32_32x32x16_bf16 v[34:49], v[164:167], v[134:137], v[34:49]
	v_mfma_f32_32x32x16_bf16 v[18:33], v[164:167], v[138:141], v[18:33]
	v_mfma_f32_32x32x16_bf16 v[2:17], v[164:167], v[142:145], v[2:17]
	s_add_i32 s43, s9, 1
	s_cmp_lg_u32 s9, 2
	s_cselect_b32 s9, s43, 0
	s_add_i32 s43, s13, 1
	s_cmp_lg_u32 s13, 2
	s_cselect_b32 s13, s43, 0
	s_add_i32 s43, s23, 1
	s_cmp_lg_u32 s23, 2
	s_cselect_b32 s23, s43, 0
	s_add_i32 s43, s12, 1
	s_waitcnt lgkmcnt(0)
	s_barrier
	s_cmp_lg_u32 s12, 2
	s_cselect_b32 s12, s43, 0
	s_add_i32 s42, s42, 1
	s_cmp_eq_u32 s21, s42
	s_cbranch_scc0 .LBB0_753
	s_setprio 0
	s_and_b64 vcc, exec, s[28:29]
	s_cbranch_vccz .LBB0_756
	s_waitcnt lgkmcnt(0)
	s_barrier
